# hgrn_b sample-state update: all 24 loads of the 8 steps issued up front, fma+store with counted vmcnt (was 8 serialized load-wait-store groups)
# speedup vs baseline: 1.0490x; 1.0020x over previous
; __device__ __forceinline__ unsigned pk2(float lo, float hi) { return pg8::cvt_pk_bf16(lo, hi); }
; __device__ __forceinline__ void hgrn_b_phase(KA A, LAS unsigned char* lds, int tid) {
;     ...
;     for (int q = (int)blockIdx.x; q < 256; q += gridDim.x) {
;         const int s0i = q >> 2, c0 = 32 * (q & 3);
;         const size_t it = 1024 + s0i; const float* S0 = A->in[4] + (size_t)s0i * 16384 + c0 * 128; float* So = A->out + O_SS + (size_t)s0i * 16384 + c0 * 128;
;         __syncthreads();
; #pragma unroll
;         for (int i = 0; i < 8; ++i) { const int e = tid + 512 * i, cl = e >> 7, v = e & 127; const float x = S0[e];
;             T[cl * 129 + v] = x; So[e] = DEC[it * 128 + c0 + cl] * x + UT[it * 16384 + c0 * 128 + e]; }
;         __syncthreads();
; #pragma unroll
;         for (int i = 0; i < 8; ++i) { const int e = tid + 512 * i, v = e >> 5, cl = e & 31; SNT[it * 16384 + v * 128 + c0 + cl] = (bf16_t)(pk2(T[cl * 129 + v], 0.f) & 0xffffu); }
;     }
.LBB0_1074:
	s_ashr_i32 s20, s29, 2
	s_lshl_b32 s18, s29, 5
	s_and_b32 s30, s18, 0x60
	s_add_i32 s18, s20, 0x400
	s_ashr_i32 s21, s20, 31
	s_ashr_i32 s19, s18, 31
	s_lshl_b64 s[22:23], s[20:21], 16
	s_add_u32 s20, s16, s22
	s_addc_u32 s21, s17, s23
	s_lshl_b32 s31, s30, 9
	s_add_u32 s20, s20, s31
	s_addc_u32 s21, s21, 0
	s_add_u32 s22, s6, s22
	s_addc_u32 s23, s7, s23
	s_add_u32 s22, s22, s31
	s_addc_u32 s23, s23, 0
	s_lshl_b64 s[24:25], s[18:19], 9
	s_add_u32 s24, s2, s24
	s_addc_u32 s25, s3, s25
	s_lshl_b32 s33, s30, 2
	s_add_u32 s24, s24, s33
	s_addc_u32 s25, s25, 0
	s_lshl_b64 s[34:35], s[18:19], 16
	s_add_u32 s33, s0, s34
	s_addc_u32 s35, s1, s35
	s_add_u32 s34, s33, s31
	s_addc_u32 s35, s35, 0
	s_waitcnt vmcnt(0)
	s_barrier
	global_load_dword v17, v0, s[20:21]
	global_load_dword v68, v30, s[24:25]
	global_load_dword v76, v0, s[34:35]
	global_load_dword v19, v0, s[20:21] offset:2048
	global_load_dword v69, v32, s[24:25]
	global_load_dword v77, v0, s[34:35] offset:2048
	global_load_dword v60, v33, s[20:21]
	global_load_dword v70, v35, s[24:25]
	global_load_dword v78, v33, s[34:35]
	global_load_dword v61, v33, s[20:21] offset:2048
	global_load_dword v71, v37, s[24:25]
	global_load_dword v79, v33, s[34:35] offset:2048
	global_load_dword v62, v38, s[20:21]
	global_load_dword v72, v40, s[24:25]
	global_load_dword v80, v38, s[34:35]
	global_load_dword v63, v38, s[20:21] offset:2048
	global_load_dword v73, v42, s[24:25]
	global_load_dword v81, v38, s[34:35] offset:2048
	global_load_dword v64, v43, s[20:21]
	global_load_dword v74, v45, s[24:25]
	global_load_dword v82, v43, s[34:35]
	global_load_dword v65, v43, s[20:21] offset:2048
	global_load_dword v75, v47, s[24:25]
	global_load_dword v83, v43, s[34:35] offset:2048
	v_lshl_add_u64 v[48:49], s[20:21], 0, v[0:1]
	v_add_co_u32_e32 v50, vcc, s26, v48
	v_lshl_add_u64 v[52:53], s[34:35], 0, v[0:1]
	s_nop 0
	v_addc_co_u32_e32 v51, vcc, 0, v49, vcc
	v_add_co_u32_e32 v54, vcc, s26, v52
	s_lshl_b64 s[18:19], s[18:19], 15
	s_nop 0
	v_addc_co_u32_e32 v55, vcc, 0, v53, vcc
	s_add_u32 s18, s4, s18
	s_addc_u32 s19, s5, s19
	v_mov_b32_e32 v7, v1
	v_mov_b32_e32 v9, v1
	v_mov_b32_e32 v11, v1
	v_mov_b32_e32 v13, v1
	v_mov_b32_e32 v15, v1
	s_waitcnt vmcnt(21)
	v_fmac_f32_e32 v76, v17, v68
	global_store_dword v0, v76, s[22:23]
	s_nop 0
	s_nop 0
	s_nop 0
	s_nop 0
	s_waitcnt vmcnt(19)
	v_fmac_f32_e32 v77, v19, v69
	global_store_dword v0, v77, s[22:23] offset:2048
	s_nop 0
	s_nop 0
	s_nop 0
	s_nop 0
	s_waitcnt vmcnt(17)
	v_fmac_f32_e32 v78, v60, v70
	global_store_dword v33, v78, s[22:23]
	s_nop 0
	s_nop 0
	s_nop 0
	s_nop 0
	v_lshl_add_u64 v[50:51], s[22:23], 0, v[0:1]
	v_add_co_u32_e32 v54, vcc, s26, v50
	s_waitcnt vmcnt(15)
	v_fmac_f32_e32 v79, v61, v71
	v_addc_co_u32_e32 v55, vcc, 0, v51, vcc
	global_store_dword v[54:55], v79, off offset:2048
	s_nop 0
	s_nop 0
	s_nop 0
	s_nop 0
	v_add_co_u32_e32 v54, vcc, s27, v48
	s_waitcnt vmcnt(13)
	v_fmac_f32_e32 v80, v62, v72
	v_addc_co_u32_e32 v55, vcc, 0, v49, vcc
	v_add_co_u32_e32 v56, vcc, s27, v52
	global_store_dword v38, v80, s[22:23]
	s_nop 0
	v_addc_co_u32_e32 v57, vcc, 0, v53, vcc
	s_nop 0
	s_nop 0
	s_nop 0
	v_add_co_u32_e32 v54, vcc, s27, v50
	s_waitcnt vmcnt(11)
	v_fmac_f32_e32 v81, v63, v73
	v_addc_co_u32_e32 v55, vcc, 0, v51, vcc
	global_store_dword v[54:55], v81, off offset:2048
	s_nop 0
	s_nop 0
	s_nop 0
	s_nop 0
	v_add_co_u32_e32 v48, vcc, s28, v48
	s_lshl_b32 s20, s30, 1
	s_nop 0
	v_addc_co_u32_e32 v49, vcc, 0, v49, vcc
	v_add_co_u32_e32 v52, vcc, s28, v52
	s_add_u32 s18, s18, s20
	s_nop 0
	v_addc_co_u32_e32 v53, vcc, 0, v53, vcc
	s_addc_u32 s19, s19, 0
	s_waitcnt vmcnt(9)
	v_fmac_f32_e32 v82, v64, v74
	global_store_dword v43, v82, s[22:23]
	s_nop 0
	s_nop 0
	s_nop 0
	v_add_co_u32_e32 v48, vcc, s28, v50
	v_mov_b32_e32 v3, v1
	s_nop 0
	v_addc_co_u32_e32 v49, vcc, 0, v51, vcc
	v_mov_b32_e32 v5, v1
	v_lshl_add_u64 v[50:51], s[18:19], 0, v[2:3]
	v_lshl_add_u64 v[52:53], v[50:51], 0, v[4:5]
	v_lshl_add_u64 v[54:55], v[50:51], 0, v[6:7]
	v_lshl_add_u64 v[56:57], v[50:51], 0, v[8:9]
	v_lshl_add_u64 v[58:59], v[50:51], 0, v[10:11]
	ds_write_b32 v29, v17
	ds_write_b32 v31, v19
	ds_write_b32 v34, v60
	ds_write_b32 v36, v61
	ds_write_b32 v39, v62
	ds_write_b32 v41, v63
	ds_write_b32 v44, v64
	s_waitcnt vmcnt(7)
	ds_write_b32 v46, v65
	v_mov_b32_e32 v17, v1
	s_waitcnt vmcnt(7)
	v_fmac_f32_e32 v83, v65, v75
	global_store_dword v[48:49], v83, off offset:2048
	s_waitcnt lgkmcnt(0)
	s_barrier
	ds_read_b32 v3, v21
	s_waitcnt lgkmcnt(0)
	v_cvt_pk_bf16_f32 v3, v3, v1
	ds_read_b32 v5, v22
	global_store_short v[52:53], v3, off
	s_waitcnt lgkmcnt(0)
	v_cvt_pk_bf16_f32 v3, v5, v1
	ds_read_b32 v5, v23
	global_store_short v[54:55], v3, off
	s_waitcnt lgkmcnt(0)
	v_cvt_pk_bf16_f32 v3, v5, v1
	ds_read_b32 v5, v24
	global_store_short v[56:57], v3, off
	s_waitcnt lgkmcnt(0)
	v_cvt_pk_bf16_f32 v3, v5, v1
	ds_read_b32 v5, v25
	global_store_short v[58:59], v3, off
	s_waitcnt lgkmcnt(0)
	v_cvt_pk_bf16_f32 v3, v5, v1
	v_lshl_add_u64 v[48:49], v[50:51], 0, v[12:13]
	ds_read_b32 v5, v26
	global_store_short v[48:49], v3, off
	s_waitcnt lgkmcnt(0)
	v_cvt_pk_bf16_f32 v3, v5, v1
	v_lshl_add_u64 v[48:49], v[50:51], 0, v[14:15]
	v_mov_b32_e32 v19, v1
	ds_read_b32 v5, v27
	global_store_short v[48:49], v3, off
	s_waitcnt lgkmcnt(0)
	v_cvt_pk_bf16_f32 v3, v5, v1
	v_lshl_add_u64 v[48:49], v[50:51], 0, v[16:17]
	v_lshl_add_u64 v[50:51], v[50:51], 0, v[18:19]
	ds_read_b32 v5, v28
	global_store_short v[48:49], v3, off
	s_waitcnt lgkmcnt(0)
	v_cvt_pk_bf16_f32 v3, v5, v1
	global_store_short v[50:51], v3, off
	s_load_dword s18, s[8:9], 0x0
	s_waitcnt lgkmcnt(0)
	s_add_i32 s29, s18, s29
	s_cmpk_gt_i32 s29, 0xff
	s_cbranch_scc0 .LBB0_1074
